# P1/P7: trailing wave group re-creates the stagger at the end of its first load segment of the next tile (both groups run epilogue, coordinate math and first loads concurrently); prologue/tail pairing
# speedup vs baseline: 1.0011x; 1.0011x over previous
.LBB0_75:
	s_and_b32 s22, 0xffff, s22
	s_cmp_lg_u32 s22, 0
	s_cselect_b64 s[22:23], -1, 0
	s_cmp_lg_u64 s[22:23], 0
	s_addc_u32 s66, s20, 0
	s_lshl_b32 s1, s1, 5
	s_and_b32 s1, s1, 0x60
	s_add_i32 m0, s62, 0x18000
	v_lshl_add_u64 v[10:11], v[10:11], 0, s[76:77]
	s_lshl_b32 s67, s21, 6
	s_lshl_b32 s22, s21, 13
	s_lshl_b32 s23, s1, 7
	s_waitcnt vmcnt(4)
	s_barrier
	global_load_lds_dwordx4 v[10:11], off
	v_lshl_add_u64 v[8:9], v[8:9], 0, s[76:77]
	s_add_i32 m0, s62, 0x1a000
	s_add_i32 s72, s62, 0x8000
	s_add_i32 s74, s62, 0xa000
	global_load_lds_dwordx4 v[8:9], off
	v_lshl_add_u64 v[6:7], v[6:7], 0, s[76:77]
	s_mov_b32 m0, s72
	s_add_u32 s20, s54, 0x40080
	global_load_lds_dwordx4 v[6:7], off
	v_lshl_add_u64 v[4:5], v[4:5], 0, s[76:77]
	s_mov_b32 m0, s74
	s_addc_u32 s21, s55, 0
	global_load_lds_dwordx4 v[4:5], off
	s_add_i32 m0, s62, 0x1c000
	v_lshl_add_u64 v[4:5], s[20:21], 0, v[2:3]
	global_load_lds_dwordx4 v[4:5], off
	v_lshl_add_u64 v[4:5], s[20:21], 0, v[0:1]
	s_add_i32 m0, s62, 0x1e000
	v_and_b32_e32 v201, 15, v13
	global_load_lds_dwordx4 v[4:5], off
	v_lshrrev_b32_e32 v4, 1, v13
	v_and_b32_e32 v4, 24, v4
	v_lshlrev_b32_e32 v5, 1, v4
	v_lshlrev_b32_e32 v6, 2, v13
	v_or_b32_e32 v238, s1, v4
	v_lshlrev_b32_e32 v4, 14, v17
	v_lshl_or_b32 v5, v201, 6, v5
	v_and_b32_e32 v6, 32, v6
	v_and_b32_e32 v4, 0xffff8000, v4
	v_bitop3_b32 v7, v5, s22, v6 bitop3:0xde
	v_bitop3_b32 v235, v5, s23, v6 bitop3:0xde
	v_lshl_add_u32 v4, v16, 11, v4
	v_and_b32_e32 v5, 1, v17
	v_lshl_or_b32 v4, v5, 6, v4
	v_lshl_add_u32 v206, v18, 1, v4
	v_bfe_u32 v20, v206, 11, 4
	v_bfe_u32 v21, v206, 15, 2
	v_and_b32_e32 v206, 0xfffe07ff, v206
	v_lshl_or_b32 v206, v20, 13, v206
	v_lshl_or_b32 v206, v21, 11, v206
	v_lshlrev_b32_e32 v4, 14, v12
	v_and_b32_e32 v4, 0xffff8000, v4
	s_waitcnt vmcnt(6)
	v_lshl_add_u32 v4, v14, 11, v4
	v_and_b32_e32 v5, 1, v12
	v_lshl_or_b32 v4, v5, 6, v4
	s_sext_i32_i16 s30, s0
	s_mov_b32 s75, 0
	v_cmp_gt_u32_e64 s[38:39], 2, v201
	v_cmp_lt_u32_e64 s[40:41], 13, v201
	v_add_u32_e32 v236, -14, v201
	v_or_b32_e32 v237, 2, v201
	s_ashr_i32 s80, s66, 31
	v_mov_b32_e32 v207, v3
	v_lshl_add_u32 v208, v15, 1, v4
	v_bfe_u32 v20, v208, 11, 4
	v_bfe_u32 v21, v208, 15, 2
	v_and_b32_e32 v208, 0xfffe07ff, v208
	v_lshl_or_b32 v208, v20, 13, v208
	v_lshl_or_b32 v208, v21, 11, v208
	v_mov_b32_e32 v209, v3
	v_add_u32_e32 v239, 0, v7
	s_mov_b64 s[48:49], s[54:55]
	s_mov_b64 s[46:47], s[52:53]
	s_barrier
	s_mov_b32 s98, 0
	s_branch .LBB0_77
.LBB0_76:
	s_or_b64 exec, exec, s[50:51]
	s_mov_b32 s98, 1
	s_and_b64 vcc, exec, s[42:43]
	s_mov_b32 s30, s0
	s_mov_b32 s50, s44
	s_mov_b64 s[54:55], s[48:49]
	s_mov_b64 s[52:53], s[46:47]
	s_cbranch_vccnz .LBB0_89

.LBB0_79:
	s_add_u32 s52, s52, 0x40080
	s_addc_u32 s53, s53, 0
	s_add_u32 s1, s54, 0x100
	s_addc_u32 s20, s55, 0
	s_mov_b32 s21, -2
	s_add_u32 s22, s52, 0xfffc0080
	s_addc_u32 s23, s53, -1
	s_add_i32 s24, 0, 0x10000
	s_add_i32 m0, s62, 0xc000
	s_cmp_eq_u32 s21, 12
	s_cselect_b32 s57, s47, s23
	s_cselect_b32 s56, s46, s22
	s_cselect_b32 s55, s49, s20
	s_cselect_b32 s54, s48, s1
	global_load_lds_dwordx4 v206, s[52:53]
	s_add_i32 m0, s62, 0xe000
	s_nop 0
	global_load_lds_dwordx4 v208, s[52:53]
	s_waitcnt lgkmcnt(8)
	s_cmp_eq_u32 s98, 0
	s_cbranch_scc1 .Lst_80
	s_cmpk_lt_u32 s59, 0x100
	s_cbranch_scc1 .Lst_80
	s_barrier
.Lst_80:
	s_barrier
	s_waitcnt lgkmcnt(0)
	v_mfma_f32_16x16x32_bf16 v[160:163], v[52:55], v[92:95], 0
	v_mfma_f32_16x16x32_bf16 v[152:155], v[60:63], v[92:95], 0
	v_mfma_f32_16x16x32_bf16 v[144:147], v[52:55], v[100:103], 0
	v_mfma_f32_16x16x32_bf16 v[140:143], v[60:63], v[100:103], 0
	v_mfma_f32_16x16x32_bf16 v[116:119], v[52:55], v[76:79], 0
	v_mfma_f32_16x16x32_bf16 v[120:123], v[60:63], v[76:79], 0
	v_mfma_f32_16x16x32_bf16 v[124:127], v[52:55], v[84:87], 0
	v_mfma_f32_16x16x32_bf16 v[128:131], v[60:63], v[84:87], 0
	v_mfma_f32_16x16x32_bf16 v[160:163], v[56:59], v[96:99], v[160:163]
	v_mfma_f32_16x16x32_bf16 v[152:155], v[64:67], v[96:99], v[152:155]
	v_mfma_f32_16x16x32_bf16 v[144:147], v[56:59], v[104:107], v[144:147]
	v_mfma_f32_16x16x32_bf16 v[140:143], v[64:67], v[104:107], v[140:143]
	v_mfma_f32_16x16x32_bf16 v[116:119], v[56:59], v[80:83], v[116:119]
	v_mfma_f32_16x16x32_bf16 v[120:123], v[64:67], v[80:83], v[120:123]
	v_mfma_f32_16x16x32_bf16 v[124:127], v[56:59], v[88:91], v[124:127]
	v_mfma_f32_16x16x32_bf16 v[128:131], v[64:67], v[88:91], v[128:131]
	s_barrier
	s_add_i32 s25, 0, 0x14000
	s_add_i32 s22, s24, s60
	s_mov_b32 m0, s22
	ds_read_b128 v[168:171], v198 offset:16384
	ds_read_b128 v[176:179], v198 offset:17408
	ds_read_b128 v[184:187], v198 offset:18432
	global_load_lds_dwordx4 v2, s[54:55]
	s_add_i32 m0, s22, 0x2000
	ds_read_b128 v[192:195], v198 offset:19456
	global_load_lds_dwordx4 v0, s[54:55]
	s_barrier
	s_waitcnt lgkmcnt(0)
	v_mfma_f32_16x16x32_bf16 v[188:191], v[168:171], v[76:79], 0
	v_mfma_f32_16x16x32_bf16 v[76:79], v[184:187], v[76:79], 0
	v_mfma_f32_16x16x32_bf16 v[188:191], v[176:179], v[80:83], v[188:191]
	v_mfma_f32_16x16x32_bf16 v[76:79], v[192:195], v[80:83], v[76:79]
	v_mfma_f32_16x16x32_bf16 v[80:83], v[168:171], v[84:87], 0
	v_mfma_f32_16x16x32_bf16 v[84:87], v[184:187], v[84:87], 0
	v_mfma_f32_16x16x32_bf16 v[80:83], v[176:179], v[88:91], v[80:83]
	v_mfma_f32_16x16x32_bf16 v[84:87], v[192:195], v[88:91], v[84:87]
	v_mfma_f32_16x16x32_bf16 v[88:91], v[168:171], v[92:95], 0
	v_mfma_f32_16x16x32_bf16 v[92:95], v[184:187], v[92:95], 0
	v_mfma_f32_16x16x32_bf16 v[88:91], v[176:179], v[96:99], v[88:91]
	v_mfma_f32_16x16x32_bf16 v[92:95], v[192:195], v[96:99], v[92:95]
	v_mfma_f32_16x16x32_bf16 v[96:99], v[168:171], v[100:103], 0
	v_mfma_f32_16x16x32_bf16 v[100:103], v[184:187], v[100:103], 0
	v_mfma_f32_16x16x32_bf16 v[96:99], v[176:179], v[104:107], v[96:99]
	v_mfma_f32_16x16x32_bf16 v[100:103], v[192:195], v[104:107], v[100:103]
	s_mov_b32 m0, s62
	s_barrier
	ds_read_b128 v[104:107], v239 offset:16384
	ds_read_b128 v[132:135], v239 offset:17408
	ds_read_b128 v[136:139], v239 offset:18432
	ds_read_b128 v[148:151], v239 offset:19456
	ds_read_b128 v[156:159], v239 offset:20480
	ds_read_b128 v[164:167], v239 offset:21504
	ds_read_b128 v[172:175], v239 offset:22528
	global_load_lds_dwordx4 v204, s[56:57]
	s_mov_b32 m0, s63
	ds_read_b128 v[180:183], v239 offset:23552
	global_load_lds_dwordx4 v202, s[56:57]
	s_barrier
	s_waitcnt lgkmcnt(0)
	v_mfma_f32_16x16x32_bf16 v[112:115], v[52:55], v[104:107], 0
	v_mfma_f32_16x16x32_bf16 v[72:75], v[60:63], v[104:107], 0
	v_mfma_f32_16x16x32_bf16 v[48:51], v[52:55], v[136:139], 0
	v_mfma_f32_16x16x32_bf16 v[40:43], v[60:63], v[136:139], 0
	v_mfma_f32_16x16x32_bf16 v[32:35], v[52:55], v[156:159], 0
	v_mfma_f32_16x16x32_bf16 v[24:27], v[60:63], v[156:159], 0
	v_mfma_f32_16x16x32_bf16 v[16:19], v[52:55], v[172:175], 0
	v_mfma_f32_16x16x32_bf16 v[12:15], v[60:63], v[172:175], 0
	v_mfma_f32_16x16x32_bf16 v[112:115], v[56:59], v[132:135], v[112:115]
	v_mfma_f32_16x16x32_bf16 v[72:75], v[64:67], v[132:135], v[72:75]
	v_mfma_f32_16x16x32_bf16 v[48:51], v[56:59], v[148:151], v[48:51]
	v_mfma_f32_16x16x32_bf16 v[40:43], v[64:67], v[148:151], v[40:43]
	v_mfma_f32_16x16x32_bf16 v[32:35], v[56:59], v[164:167], v[32:35]
	v_mfma_f32_16x16x32_bf16 v[24:27], v[64:67], v[164:167], v[24:27]
	v_mfma_f32_16x16x32_bf16 v[16:19], v[56:59], v[180:183], v[16:19]
	v_mfma_f32_16x16x32_bf16 v[12:15], v[64:67], v[180:183], v[12:15]
	s_barrier
	s_add_i32 s24, s25, s60
	s_mov_b32 m0, s24
	s_add_u32 s22, s54, 0x40000
	s_addc_u32 s23, s55, 0
	global_load_lds_dwordx4 v2, s[22:23]
	s_add_i32 m0, s24, 0x2000
	s_waitcnt vmcnt(5)
	global_load_lds_dwordx4 v0, s[22:23]
	s_barrier
	v_mfma_f32_16x16x32_bf16 v[44:47], v[168:171], v[136:139], 0
	v_mfma_f32_16x16x32_bf16 v[36:39], v[184:187], v[136:139], 0
	v_mfma_f32_16x16x32_bf16 v[28:31], v[168:171], v[156:159], 0
	v_mfma_f32_16x16x32_bf16 v[20:23], v[184:187], v[156:159], 0
	v_mfma_f32_16x16x32_bf16 v[8:11], v[168:171], v[172:175], 0
	v_mfma_f32_16x16x32_bf16 v[4:7], v[184:187], v[172:175], 0
	v_mfma_f32_16x16x32_bf16 v[52:55], v[168:171], v[104:107], 0
	v_mfma_f32_16x16x32_bf16 v[56:59], v[184:187], v[104:107], 0
	v_mfma_f32_16x16x32_bf16 v[44:47], v[176:179], v[148:151], v[44:47]
	v_mfma_f32_16x16x32_bf16 v[36:39], v[192:195], v[148:151], v[36:39]
	v_mfma_f32_16x16x32_bf16 v[28:31], v[176:179], v[164:167], v[28:31]
	v_mfma_f32_16x16x32_bf16 v[20:23], v[192:195], v[164:167], v[20:23]
	v_mfma_f32_16x16x32_bf16 v[8:11], v[176:179], v[180:183], v[8:11]
	v_mfma_f32_16x16x32_bf16 v[4:7], v[192:195], v[180:183], v[4:7]
	v_mfma_f32_16x16x32_bf16 v[52:55], v[176:179], v[132:135], v[52:55]
	v_mfma_f32_16x16x32_bf16 v[56:59], v[192:195], v[132:135], v[56:59]
	s_add_i32 s24, 0, 0x18000
	s_barrier
	ds_read_b128 v[60:63], v198 offset:32768
	ds_read_b128 v[64:67], v198 offset:33792
	ds_read_b128 v[68:71], v198 offset:34816
	ds_read_b128 v[104:107], v198 offset:35840
	s_add_u32 s22, s56, 0x40000
	s_addc_u32 s23, s57, 0
	s_mov_b32 m0, s64
	ds_read_b128 v[108:111], v239 offset:32768
	ds_read_b128 v[132:135], v239 offset:33792
	ds_read_b128 v[136:139], v239 offset:34816
	ds_read_b128 v[148:151], v239 offset:35840
	ds_read_b128 v[210:213], v239 offset:36864
	ds_read_b128 v[214:217], v239 offset:37888
	ds_read_b128 v[240:243], v239 offset:38912
	global_load_lds_dwordx4 v204, s[22:23]
	s_mov_b32 m0, s65
	ds_read_b128 v[244:247], v239 offset:39936
	global_load_lds_dwordx4 v202, s[22:23]
	s_waitcnt lgkmcnt(8)
	s_barrier
	s_waitcnt lgkmcnt(0)
	v_mfma_f32_16x16x32_bf16 v[116:119], v[60:63], v[108:111], v[116:119]
	v_mfma_f32_16x16x32_bf16 v[192:195], v[64:67], v[132:135], v[116:119]
	v_mfma_f32_16x16x32_bf16 v[116:119], v[68:71], v[108:111], v[120:123]
	v_mfma_f32_16x16x32_bf16 v[184:187], v[104:107], v[132:135], v[116:119]
	v_mfma_f32_16x16x32_bf16 v[116:119], v[60:63], v[136:139], v[124:127]
	v_mfma_f32_16x16x32_bf16 v[176:179], v[64:67], v[148:151], v[116:119]
	v_mfma_f32_16x16x32_bf16 v[116:119], v[68:71], v[136:139], v[128:131]
	v_mfma_f32_16x16x32_bf16 v[168:171], v[104:107], v[148:151], v[116:119]
	v_mfma_f32_16x16x32_bf16 v[116:119], v[60:63], v[210:213], v[160:163]
	v_mfma_f32_16x16x32_bf16 v[160:163], v[64:67], v[214:217], v[116:119]
	v_mfma_f32_16x16x32_bf16 v[116:119], v[68:71], v[210:213], v[152:155]
	v_mfma_f32_16x16x32_bf16 v[152:155], v[104:107], v[214:217], v[116:119]
	v_mfma_f32_16x16x32_bf16 v[116:119], v[60:63], v[240:243], v[144:147]
	v_mfma_f32_16x16x32_bf16 v[144:147], v[64:67], v[244:247], v[116:119]
	v_mfma_f32_16x16x32_bf16 v[116:119], v[68:71], v[240:243], v[140:143]
	v_mfma_f32_16x16x32_bf16 v[140:143], v[104:107], v[244:247], v[116:119]
	s_barrier
	s_add_i32 s25, 0, 0x1c000
	s_add_i32 s22, s24, s60
	s_mov_b32 m0, s22
	ds_read_b128 v[116:119], v198 offset:49152
	ds_read_b128 v[120:123], v198 offset:50176
	ds_read_b128 v[124:127], v198 offset:51200
	s_add_u32 s98, s54, 0x80
	s_addc_u32 s99, s55, 0
	global_load_lds_dwordx4 v2, s[98:99]
	s_add_i32 m0, s22, 0x2000
	ds_read_b128 v[128:131], v198 offset:52224
	global_load_lds_dwordx4 v0, s[98:99]
	s_barrier
	s_waitcnt lgkmcnt(0)
	v_mfma_f32_16x16x32_bf16 v[76:79], v[124:127], v[108:111], v[76:79]
	v_mfma_f32_16x16x32_bf16 v[180:183], v[128:131], v[132:135], v[76:79]
	v_mfma_f32_16x16x32_bf16 v[76:79], v[116:119], v[136:139], v[80:83]
	v_mfma_f32_16x16x32_bf16 v[172:175], v[120:123], v[148:151], v[76:79]
	v_mfma_f32_16x16x32_bf16 v[76:79], v[124:127], v[136:139], v[84:87]
	v_mfma_f32_16x16x32_bf16 v[156:159], v[116:119], v[108:111], v[188:191]
	v_mfma_f32_16x16x32_bf16 v[164:167], v[128:131], v[148:151], v[76:79]
	v_mfma_f32_16x16x32_bf16 v[76:79], v[116:119], v[210:213], v[88:91]
	v_mfma_f32_16x16x32_bf16 v[188:191], v[120:123], v[132:135], v[156:159]
	v_mfma_f32_16x16x32_bf16 v[156:159], v[120:123], v[214:217], v[76:79]
	v_mfma_f32_16x16x32_bf16 v[76:79], v[124:127], v[210:213], v[92:95]
	v_mfma_f32_16x16x32_bf16 v[148:151], v[128:131], v[214:217], v[76:79]
	v_mfma_f32_16x16x32_bf16 v[76:79], v[116:119], v[240:243], v[96:99]
	v_mfma_f32_16x16x32_bf16 v[136:139], v[120:123], v[244:247], v[76:79]
	v_mfma_f32_16x16x32_bf16 v[76:79], v[124:127], v[240:243], v[100:103]
	v_mfma_f32_16x16x32_bf16 v[132:135], v[128:131], v[244:247], v[76:79]
	s_mov_b32 m0, s72
	s_barrier
	s_nop 2
	ds_read_b128 v[76:79], v239 offset:49152
	ds_read_b128 v[80:83], v239 offset:50176
	ds_read_b128 v[84:87], v239 offset:51200
	ds_read_b128 v[88:91], v239 offset:52224
	ds_read_b128 v[92:95], v239 offset:53248
	ds_read_b128 v[96:99], v239 offset:54272
	ds_read_b128 v[100:103], v239 offset:55296
	s_add_u32 s98, s56, 0x80
	s_addc_u32 s99, s57, 0
	global_load_lds_dwordx4 v204, s[98:99]
	s_mov_b32 m0, s74
	ds_read_b128 v[210:213], v239 offset:56320
	global_load_lds_dwordx4 v202, s[98:99]
	s_barrier
	s_waitcnt lgkmcnt(0)
	v_mfma_f32_16x16x32_bf16 v[108:111], v[60:63], v[76:79], v[112:115]
	v_mfma_f32_16x16x32_bf16 v[72:75], v[68:71], v[76:79], v[72:75]
	v_mfma_f32_16x16x32_bf16 v[48:51], v[60:63], v[84:87], v[48:51]
	v_mfma_f32_16x16x32_bf16 v[40:43], v[68:71], v[84:87], v[40:43]
	v_mfma_f32_16x16x32_bf16 v[32:35], v[60:63], v[92:95], v[32:35]
	v_mfma_f32_16x16x32_bf16 v[24:27], v[68:71], v[92:95], v[24:27]
	v_mfma_f32_16x16x32_bf16 v[16:19], v[60:63], v[100:103], v[16:19]
	v_mfma_f32_16x16x32_bf16 v[12:15], v[68:71], v[100:103], v[12:15]
	v_mfma_f32_16x16x32_bf16 v[112:115], v[64:67], v[80:83], v[108:111]
	v_mfma_f32_16x16x32_bf16 v[72:75], v[104:107], v[80:83], v[72:75]
	v_mfma_f32_16x16x32_bf16 v[48:51], v[64:67], v[88:91], v[48:51]
	v_mfma_f32_16x16x32_bf16 v[40:43], v[104:107], v[88:91], v[40:43]
	v_mfma_f32_16x16x32_bf16 v[32:35], v[64:67], v[96:99], v[32:35]
	v_mfma_f32_16x16x32_bf16 v[24:27], v[104:107], v[96:99], v[24:27]
	v_mfma_f32_16x16x32_bf16 v[16:19], v[64:67], v[210:213], v[16:19]
	v_mfma_f32_16x16x32_bf16 v[12:15], v[104:107], v[210:213], v[12:15]
	s_barrier
	s_add_i32 s24, s25, s60
	s_mov_b32 m0, s24
	s_add_u32 s22, s54, 0x40080
	s_addc_u32 s23, s55, 0
	global_load_lds_dwordx4 v2, s[22:23]
	s_add_i32 m0, s24, 0x2000
	s_waitcnt vmcnt(5)
	global_load_lds_dwordx4 v0, s[22:23]
	s_barrier
	v_mfma_f32_16x16x32_bf16 v[52:55], v[116:119], v[76:79], v[52:55]
	v_mfma_f32_16x16x32_bf16 v[108:111], v[120:123], v[80:83], v[52:55]
	v_mfma_f32_16x16x32_bf16 v[52:55], v[124:127], v[76:79], v[56:59]
	v_mfma_f32_16x16x32_bf16 v[44:47], v[116:119], v[84:87], v[44:47]
	v_mfma_f32_16x16x32_bf16 v[36:39], v[124:127], v[84:87], v[36:39]
	v_mfma_f32_16x16x32_bf16 v[28:31], v[116:119], v[92:95], v[28:31]
	v_mfma_f32_16x16x32_bf16 v[20:23], v[124:127], v[92:95], v[20:23]
	v_mfma_f32_16x16x32_bf16 v[8:11], v[116:119], v[100:103], v[8:11]
	v_mfma_f32_16x16x32_bf16 v[4:7], v[124:127], v[100:103], v[4:7]
	v_mfma_f32_16x16x32_bf16 v[68:71], v[128:131], v[80:83], v[52:55]
	v_mfma_f32_16x16x32_bf16 v[44:47], v[120:123], v[88:91], v[44:47]
	v_mfma_f32_16x16x32_bf16 v[36:39], v[128:131], v[88:91], v[36:39]
	v_mfma_f32_16x16x32_bf16 v[28:31], v[120:123], v[96:99], v[28:31]
	v_mfma_f32_16x16x32_bf16 v[20:23], v[128:131], v[96:99], v[20:23]
	v_mfma_f32_16x16x32_bf16 v[8:11], v[120:123], v[210:213], v[8:11]
	v_mfma_f32_16x16x32_bf16 v[4:7], v[128:131], v[210:213], v[4:7]
	s_add_i32 s21, s21, 2
	s_add_u32 s52, s52, 0x100
	s_addc_u32 s53, s53, 0
	s_add_u32 s1, s1, 0x100
	s_addc_u32 s20, s20, 0
	s_cmp_gt_u32 s21, 13
	s_barrier
	s_cbranch_scc1 .Lpeel_out_80

.LBB0_89:
	s_waitcnt vmcnt(0)
	v_readlane_b32 s74, v255, 1
	s_cmpk_gt_u32 s59, 0xff
	v_readlane_b32 s70, v254, 58
	v_readlane_b32 s75, v255, 2
	s_mov_b32 s67, 0x8000
	v_xor_b32_e32 v219, 2, v218
	v_xor_b32_e32 v235, 4, v218
	s_cbranch_scc1 .LBB0_91
.LBB0_91:
	v_readlane_b32 s80, v254, 59
	v_readlane_b32 s81, v254, 60
	s_barrier

.LBB0_390:
	s_and_b32 s21, s21, 3
	s_add_i32 m0, s74, 0x18000
	v_lshl_add_u64 v[10:11], v[10:11], 0, s[76:77]
	s_lshl_b32 s11, s22, 6
	s_lshl_b32 s24, s22, 13
	s_lshl_b32 s49, s21, 5
	s_lshl_b32 s25, s21, 12
	s_waitcnt vmcnt(4)
	s_barrier
	global_load_lds_dwordx4 v[10:11], off
	v_lshl_add_u64 v[8:9], v[8:9], 0, s[76:77]
	s_add_i32 m0, s74, 0x1a000
	s_add_i32 s48, s74, 0x8000
	s_add_i32 s50, s74, 0xa000
	global_load_lds_dwordx4 v[8:9], off
	v_lshl_add_u64 v[6:7], v[6:7], 0, s[76:77]
	s_mov_b32 m0, s48
	s_add_u32 s22, s44, 0x40080
	global_load_lds_dwordx4 v[6:7], off
	v_lshl_add_u64 v[4:5], v[4:5], 0, s[76:77]
	s_mov_b32 m0, s50
	s_addc_u32 s23, s45, 0
	global_load_lds_dwordx4 v[4:5], off
	s_add_i32 m0, s74, 0x1c000
	v_lshl_add_u64 v[4:5], s[22:23], 0, v[176:177]
	global_load_lds_dwordx4 v[4:5], off
	v_lshl_add_u64 v[4:5], s[22:23], 0, v[180:181]
	s_add_i32 m0, s74, 0x1e000
	v_and_b32_e32 v183, 15, v2
	global_load_lds_dwordx4 v[4:5], off
	v_lshrrev_b32_e32 v4, 1, v2
	v_and_b32_e32 v182, 24, v4
	v_lshlrev_b32_e32 v4, 1, v182
	v_lshlrev_b32_e32 v2, 2, v2
	s_cmp_eq_u32 s21, 0
	v_lshl_or_b32 v4, v183, 6, v4
	v_and_b32_e32 v2, 32, v2
	s_cselect_b64 s[36:37], -1, 0
	s_cmpk_lt_u32 s20, 0x100
	v_bitop3_b32 v6, v4, s24, v2 bitop3:0xde
	v_bitop3_b32 v187, v4, s25, v2 bitop3:0xde
	s_cselect_b64 s[2:3], -1, 0
	v_readlane_b32 s12, v254, 42
	v_writelane_b32 v255, s2, 3
	v_readlane_b32 s20, v254, 50
	v_readlane_b32 s21, v254, 51
	v_or_b32_e32 v2, s49, v182
	v_writelane_b32 v255, s3, 4
	v_readlane_b32 s20, v252, 52
	v_or_b32_e32 v201, 0xfffff800, v2
	v_lshlrev_b32_e32 v2, 2, v182
	v_readlane_b32 s24, v254, 54
	v_readlane_b32 s25, v254, 55
	v_readlane_b32 s21, v252, 53
	v_readlane_b32 s2, v255, 1
	v_lshl_add_u64 v[188:189], s[24:25], 0, v[2:3]
	v_lshl_add_u64 v[190:191], s[20:21], 0, v[2:3]
	v_readlane_b32 s3, v255, 2
	v_lshlrev_b32_e32 v2, 14, v12
	v_add_u32_e32 v184, -13, v183
	v_mov_b64_e32 v[4:5], s[2:3]
	v_and_b32_e32 v2, 0xffff8000, v2
	v_mad_u64_u32 v[192:193], s[20:21], v184, s68, v[4:5]
	v_lshl_add_u32 v2, v13, 11, v2
	v_and_b32_e32 v4, 1, v12
	v_lshl_or_b32 v2, v4, 6, v2
	v_lshl_add_u32 v194, v14, 1, v2
	v_bfe_u32 v20, v194, 11, 4
	v_bfe_u32 v21, v194, 15, 2
	v_and_b32_e32 v194, 0xfffe07ff, v194
	v_lshl_or_b32 v194, v20, 13, v194
	v_lshl_or_b32 v194, v21, 11, v194
	v_lshlrev_b32_e32 v2, 14, v15
	v_and_b32_e32 v2, 0xffff8000, v2
	s_waitcnt vmcnt(6)
	v_lshl_add_u32 v2, v16, 11, v2
	v_and_b32_e32 v4, 1, v15
	v_lshl_or_b32 v185, v183, 2, s11
	v_lshl_or_b32 v2, v4, 6, v2
	s_mov_b32 s51, 0
	v_or_b32_e32 v241, 1, v185
	v_or_b32_e32 v219, 2, v185
	v_or_b32_e32 v235, 3, v185
	v_add_u32_e32 v221, 0x80, v185
	v_add_u32_e32 v224, 0x81, v185
	v_add_u32_e32 v238, 0x82, v185
	v_add_u32_e32 v239, 0x83, v185
	v_cmp_gt_u32_e64 s[38:39], 3, v183
	v_cmp_lt_u32_e64 s[40:41], 12, v183
	v_add_u32_e32 v186, 3, v183
	s_waitcnt lgkmcnt(0)
	s_ashr_i32 s31, s10, 31
	s_ashr_i32 s78, s66, 31
	v_mov_b32_e32 v195, v3
	v_lshl_add_u32 v202, v17, 1, v2
	v_bfe_u32 v20, v202, 11, 4
	v_bfe_u32 v21, v202, 15, 2
	v_and_b32_e32 v202, 0xfffe07ff, v202
	v_lshl_or_b32 v202, v20, 13, v202
	v_lshl_or_b32 v202, v21, 11, v202
	v_mov_b32_e32 v203, v3
	v_add_u32_e32 v240, 0, v6
	s_mov_b64 s[56:57], s[0:1]
	s_mov_b64 s[58:59], s[44:45]
	s_barrier
	v_readlane_b32 s13, v254, 43
	v_readlane_b32 s14, v254, 44
	v_readlane_b32 s15, v254, 45
	v_readlane_b32 s16, v254, 46
	v_readlane_b32 s17, v254, 47
	v_readlane_b32 s18, v254, 48
	v_readlane_b32 s19, v254, 49
	v_readlane_b32 s22, v254, 52
	v_readlane_b32 s23, v254, 53
	v_readlane_b32 s26, v254, 56
	v_readlane_b32 s27, v254, 57
	s_mov_b32 s98, 0
	s_branch .LBB0_420

.LBB0_419:
	s_mov_b32 s98, 1
	s_and_b64 vcc, exec, s[42:43]
	s_mov_b32 s61, s54
	s_mov_b32 s60, s52
	s_mov_b64 s[44:45], s[58:59]
	s_mov_b64 s[0:1], s[56:57]
	s_cbranch_vccnz .LBB0_499

.LBB0_426:
	s_add_u32 s0, s0, 0x40080
	s_addc_u32 s1, s1, 0
	s_add_u32 s20, s44, 0x100
	s_addc_u32 s21, s45, 0
	s_mov_b32 s22, -2
	s_add_u32 s23, s0, 0xfffc0080
	s_addc_u32 s24, s1, -1
	s_add_i32 s25, 0, 0x10000
	s_add_i32 m0, s74, 0xc000
	s_cmp_eq_u32 s22, 12
	s_cselect_b32 s47, s57, s24
	s_cselect_b32 s46, s56, s23
	s_cselect_b32 s45, s59, s21
	s_cselect_b32 s44, s58, s20
	global_load_lds_dwordx4 v194, s[0:1]
	s_add_i32 m0, s74, 0xe000
	s_nop 0
	global_load_lds_dwordx4 v202, s[0:1]
	s_waitcnt lgkmcnt(8)
	s_cmp_eq_u32 s98, 0
	s_cbranch_scc1 .Lst_427
	v_readlane_b32 s99, v255, 3
	s_nop 0
	s_cmp_lg_u32 s99, 0
	s_cbranch_scc1 .Lst_427
	s_barrier
.Lst_427:
	s_barrier
	s_waitcnt lgkmcnt(0)
	v_mfma_f32_16x16x32_bf16 v[128:131], v[132:135], v[148:151], 0
	v_mfma_f32_16x16x32_bf16 v[124:127], v[140:143], v[148:151], 0
	v_mfma_f32_16x16x32_bf16 v[120:123], v[132:135], v[156:159], 0
	v_mfma_f32_16x16x32_bf16 v[116:119], v[140:143], v[156:159], 0
	v_mfma_f32_16x16x32_bf16 v[112:115], v[132:135], v[164:167], 0
	v_mfma_f32_16x16x32_bf16 v[108:111], v[140:143], v[164:167], 0
	v_mfma_f32_16x16x32_bf16 v[104:107], v[132:135], v[172:175], 0
	v_mfma_f32_16x16x32_bf16 v[100:103], v[140:143], v[172:175], 0
	v_mfma_f32_16x16x32_bf16 v[128:131], v[136:139], v[152:155], v[128:131]
	v_mfma_f32_16x16x32_bf16 v[124:127], v[144:147], v[152:155], v[124:127]
	v_mfma_f32_16x16x32_bf16 v[120:123], v[136:139], v[160:163], v[120:123]
	v_mfma_f32_16x16x32_bf16 v[116:119], v[144:147], v[160:163], v[116:119]
	v_mfma_f32_16x16x32_bf16 v[112:115], v[136:139], v[168:171], v[112:115]
	v_mfma_f32_16x16x32_bf16 v[108:111], v[144:147], v[168:171], v[108:111]
	v_mfma_f32_16x16x32_bf16 v[104:107], v[136:139], v[204:207], v[104:107]
	v_mfma_f32_16x16x32_bf16 v[100:103], v[144:147], v[204:207], v[100:103]
	s_barrier
	s_add_i32 s23, 0, 0x14000
	s_add_i32 s24, s25, s67
	s_mov_b32 m0, s24
	ds_read_b128 v[208:211], v216 offset:16384
	ds_read_b128 v[212:215], v216 offset:17408
	ds_read_b128 v[242:245], v216 offset:18432
	global_load_lds_dwordx4 v176, s[44:45]
	s_add_i32 m0, s24, 0x2000
	ds_read_b128 v[246:249], v216 offset:19456
	global_load_lds_dwordx4 v180, s[44:45]
	s_barrier
	s_waitcnt lgkmcnt(0)
	v_mfma_f32_16x16x32_bf16 v[64:67], v[208:211], v[148:151], 0
	v_mfma_f32_16x16x32_bf16 v[60:63], v[242:245], v[148:151], 0
	v_mfma_f32_16x16x32_bf16 v[56:59], v[208:211], v[156:159], 0
	v_mfma_f32_16x16x32_bf16 v[52:55], v[242:245], v[156:159], 0
	v_mfma_f32_16x16x32_bf16 v[48:51], v[208:211], v[164:167], 0
	v_mfma_f32_16x16x32_bf16 v[44:47], v[242:245], v[164:167], 0
	v_mfma_f32_16x16x32_bf16 v[40:43], v[208:211], v[172:175], 0
	v_mfma_f32_16x16x32_bf16 v[36:39], v[242:245], v[172:175], 0
	v_mfma_f32_16x16x32_bf16 v[64:67], v[212:215], v[152:155], v[64:67]
	v_mfma_f32_16x16x32_bf16 v[60:63], v[246:249], v[152:155], v[60:63]
	v_mfma_f32_16x16x32_bf16 v[56:59], v[212:215], v[160:163], v[56:59]
	v_mfma_f32_16x16x32_bf16 v[52:55], v[246:249], v[160:163], v[52:55]
	v_mfma_f32_16x16x32_bf16 v[48:51], v[212:215], v[168:171], v[48:51]
	v_mfma_f32_16x16x32_bf16 v[44:47], v[246:249], v[168:171], v[44:47]
	v_mfma_f32_16x16x32_bf16 v[40:43], v[212:215], v[204:207], v[40:43]
	v_mfma_f32_16x16x32_bf16 v[36:39], v[246:249], v[204:207], v[36:39]
	s_mov_b32 m0, s74
	s_barrier
	ds_read_b128 v[148:151], v240 offset:16384
	ds_read_b128 v[152:155], v240 offset:17408
	ds_read_b128 v[156:159], v240 offset:18432
	ds_read_b128 v[160:163], v240 offset:19456
	ds_read_b128 v[164:167], v240 offset:20480
	ds_read_b128 v[168:171], v240 offset:21504
	ds_read_b128 v[172:175], v240 offset:22528
	global_load_lds_dwordx4 v0, s[46:47]
	s_mov_b32 m0, s75
	ds_read_b128 v[204:207], v240 offset:23552
	global_load_lds_dwordx4 v178, s[46:47]
	s_barrier
	s_waitcnt lgkmcnt(0)
	v_mfma_f32_16x16x32_bf16 v[96:99], v[132:135], v[148:151], 0
	v_mfma_f32_16x16x32_bf16 v[92:95], v[140:143], v[148:151], 0
	v_mfma_f32_16x16x32_bf16 v[88:91], v[132:135], v[156:159], 0
	v_mfma_f32_16x16x32_bf16 v[84:87], v[140:143], v[156:159], 0
	v_mfma_f32_16x16x32_bf16 v[80:83], v[132:135], v[164:167], 0
	v_mfma_f32_16x16x32_bf16 v[76:79], v[140:143], v[164:167], 0
	v_mfma_f32_16x16x32_bf16 v[72:75], v[132:135], v[172:175], 0
	v_mfma_f32_16x16x32_bf16 v[68:71], v[140:143], v[172:175], 0
	v_mfma_f32_16x16x32_bf16 v[96:99], v[136:139], v[152:155], v[96:99]
	v_mfma_f32_16x16x32_bf16 v[92:95], v[144:147], v[152:155], v[92:95]
	v_mfma_f32_16x16x32_bf16 v[88:91], v[136:139], v[160:163], v[88:91]
	v_mfma_f32_16x16x32_bf16 v[84:87], v[144:147], v[160:163], v[84:87]
	v_mfma_f32_16x16x32_bf16 v[80:83], v[136:139], v[168:171], v[80:83]
	v_mfma_f32_16x16x32_bf16 v[76:79], v[144:147], v[168:171], v[76:79]
	v_mfma_f32_16x16x32_bf16 v[72:75], v[136:139], v[204:207], v[72:75]
	v_mfma_f32_16x16x32_bf16 v[68:71], v[144:147], v[204:207], v[68:71]
	s_barrier
	s_add_i32 s23, s23, s67
	s_mov_b32 m0, s23
	s_add_u32 s24, s44, 0x40000
	s_addc_u32 s25, s45, 0
	global_load_lds_dwordx4 v176, s[24:25]
	s_add_i32 m0, s23, 0x2000
	s_waitcnt vmcnt(5)
	global_load_lds_dwordx4 v180, s[24:25]
	s_barrier
	v_mfma_f32_16x16x32_bf16 v[32:35], v[208:211], v[148:151], 0
	v_mfma_f32_16x16x32_bf16 v[28:31], v[242:245], v[148:151], 0
	v_mfma_f32_16x16x32_bf16 v[24:27], v[208:211], v[156:159], 0
	v_mfma_f32_16x16x32_bf16 v[20:23], v[242:245], v[156:159], 0
	v_mfma_f32_16x16x32_bf16 v[16:19], v[208:211], v[164:167], 0
	v_mfma_f32_16x16x32_bf16 v[12:15], v[242:245], v[164:167], 0
	v_mfma_f32_16x16x32_bf16 v[8:11], v[208:211], v[172:175], 0
	v_mfma_f32_16x16x32_bf16 v[4:7], v[242:245], v[172:175], 0
	v_mfma_f32_16x16x32_bf16 v[32:35], v[212:215], v[152:155], v[32:35]
	v_mfma_f32_16x16x32_bf16 v[28:31], v[246:249], v[152:155], v[28:31]
	v_mfma_f32_16x16x32_bf16 v[24:27], v[212:215], v[160:163], v[24:27]
	v_mfma_f32_16x16x32_bf16 v[20:23], v[246:249], v[160:163], v[20:23]
	v_mfma_f32_16x16x32_bf16 v[16:19], v[212:215], v[168:171], v[16:19]
	v_mfma_f32_16x16x32_bf16 v[12:15], v[246:249], v[168:171], v[12:15]
	v_mfma_f32_16x16x32_bf16 v[8:11], v[212:215], v[204:207], v[8:11]
	v_mfma_f32_16x16x32_bf16 v[4:7], v[246:249], v[204:207], v[4:7]
	s_add_i32 s23, 0, 0x18000
	s_barrier
	ds_read_b128 v[132:135], v216 offset:32768
	ds_read_b128 v[136:139], v216 offset:33792
	ds_read_b128 v[140:143], v216 offset:34816
	ds_read_b128 v[144:147], v216 offset:35840
	s_add_u32 s24, s46, 0x40000
	s_addc_u32 s25, s47, 0
	s_mov_b32 m0, s82
	ds_read_b128 v[148:151], v240 offset:32768
	ds_read_b128 v[152:155], v240 offset:33792
	ds_read_b128 v[156:159], v240 offset:34816
	ds_read_b128 v[160:163], v240 offset:35840
	ds_read_b128 v[164:167], v240 offset:36864
	ds_read_b128 v[168:171], v240 offset:37888
	ds_read_b128 v[172:175], v240 offset:38912
	global_load_lds_dwordx4 v0, s[24:25]
	s_mov_b32 m0, s83
	ds_read_b128 v[204:207], v240 offset:39936
	global_load_lds_dwordx4 v178, s[24:25]
	s_waitcnt lgkmcnt(8)
	s_barrier
	s_waitcnt lgkmcnt(0)
	v_mfma_f32_16x16x32_bf16 v[128:131], v[132:135], v[148:151], v[128:131]
	v_mfma_f32_16x16x32_bf16 v[124:127], v[140:143], v[148:151], v[124:127]
	v_mfma_f32_16x16x32_bf16 v[120:123], v[132:135], v[156:159], v[120:123]
	v_mfma_f32_16x16x32_bf16 v[116:119], v[140:143], v[156:159], v[116:119]
	v_mfma_f32_16x16x32_bf16 v[112:115], v[132:135], v[164:167], v[112:115]
	v_mfma_f32_16x16x32_bf16 v[108:111], v[140:143], v[164:167], v[108:111]
	v_mfma_f32_16x16x32_bf16 v[104:107], v[132:135], v[172:175], v[104:107]
	v_mfma_f32_16x16x32_bf16 v[100:103], v[140:143], v[172:175], v[100:103]
	v_mfma_f32_16x16x32_bf16 v[128:131], v[136:139], v[152:155], v[128:131]
	v_mfma_f32_16x16x32_bf16 v[124:127], v[144:147], v[152:155], v[124:127]
	v_mfma_f32_16x16x32_bf16 v[120:123], v[136:139], v[160:163], v[120:123]
	v_mfma_f32_16x16x32_bf16 v[116:119], v[144:147], v[160:163], v[116:119]
	v_mfma_f32_16x16x32_bf16 v[112:115], v[136:139], v[168:171], v[112:115]
	v_mfma_f32_16x16x32_bf16 v[108:111], v[144:147], v[168:171], v[108:111]
	v_mfma_f32_16x16x32_bf16 v[104:107], v[136:139], v[204:207], v[104:107]
	v_mfma_f32_16x16x32_bf16 v[100:103], v[144:147], v[204:207], v[100:103]
	s_barrier
	s_add_i32 s26, 0, 0x1c000
	s_add_i32 s23, s23, s67
	s_mov_b32 m0, s23
	ds_read_b128 v[208:211], v216 offset:49152
	ds_read_b128 v[212:215], v216 offset:50176
	ds_read_b128 v[242:245], v216 offset:51200
	s_add_u32 s98, s44, 0x80
	s_addc_u32 s99, s45, 0
	global_load_lds_dwordx4 v176, s[98:99]
	s_add_i32 m0, s23, 0x2000
	ds_read_b128 v[246:249], v216 offset:52224
	global_load_lds_dwordx4 v180, s[98:99]
	s_barrier
	s_waitcnt lgkmcnt(0)
	v_mfma_f32_16x16x32_bf16 v[64:67], v[208:211], v[148:151], v[64:67]
	v_mfma_f32_16x16x32_bf16 v[60:63], v[242:245], v[148:151], v[60:63]
	v_mfma_f32_16x16x32_bf16 v[56:59], v[208:211], v[156:159], v[56:59]
	v_mfma_f32_16x16x32_bf16 v[52:55], v[242:245], v[156:159], v[52:55]
	v_mfma_f32_16x16x32_bf16 v[48:51], v[208:211], v[164:167], v[48:51]
	v_mfma_f32_16x16x32_bf16 v[44:47], v[242:245], v[164:167], v[44:47]
	v_mfma_f32_16x16x32_bf16 v[40:43], v[208:211], v[172:175], v[40:43]
	v_mfma_f32_16x16x32_bf16 v[36:39], v[242:245], v[172:175], v[36:39]
	v_mfma_f32_16x16x32_bf16 v[64:67], v[212:215], v[152:155], v[64:67]
	v_mfma_f32_16x16x32_bf16 v[60:63], v[246:249], v[152:155], v[60:63]
	v_mfma_f32_16x16x32_bf16 v[56:59], v[212:215], v[160:163], v[56:59]
	v_mfma_f32_16x16x32_bf16 v[52:55], v[246:249], v[160:163], v[52:55]
	v_mfma_f32_16x16x32_bf16 v[48:51], v[212:215], v[168:171], v[48:51]
	v_mfma_f32_16x16x32_bf16 v[44:47], v[246:249], v[168:171], v[44:47]
	v_mfma_f32_16x16x32_bf16 v[40:43], v[212:215], v[204:207], v[40:43]
	v_mfma_f32_16x16x32_bf16 v[36:39], v[246:249], v[204:207], v[36:39]
	s_mov_b32 m0, s48
	s_barrier
	ds_read_b128 v[148:151], v240 offset:49152
	ds_read_b128 v[152:155], v240 offset:50176
	ds_read_b128 v[156:159], v240 offset:51200
	ds_read_b128 v[160:163], v240 offset:52224
	ds_read_b128 v[164:167], v240 offset:53248
	ds_read_b128 v[168:171], v240 offset:54272
	ds_read_b128 v[172:175], v240 offset:55296
	s_add_u32 s98, s46, 0x80
	s_addc_u32 s99, s47, 0
	global_load_lds_dwordx4 v0, s[98:99]
	s_mov_b32 m0, s50
	ds_read_b128 v[204:207], v240 offset:56320
	global_load_lds_dwordx4 v178, s[98:99]
	s_barrier
	s_waitcnt lgkmcnt(0)
	v_mfma_f32_16x16x32_bf16 v[96:99], v[132:135], v[148:151], v[96:99]
	v_mfma_f32_16x16x32_bf16 v[92:95], v[140:143], v[148:151], v[92:95]
	v_mfma_f32_16x16x32_bf16 v[88:91], v[132:135], v[156:159], v[88:91]
	v_mfma_f32_16x16x32_bf16 v[84:87], v[140:143], v[156:159], v[84:87]
	v_mfma_f32_16x16x32_bf16 v[80:83], v[132:135], v[164:167], v[80:83]
	v_mfma_f32_16x16x32_bf16 v[76:79], v[140:143], v[164:167], v[76:79]
	v_mfma_f32_16x16x32_bf16 v[72:75], v[132:135], v[172:175], v[72:75]
	v_mfma_f32_16x16x32_bf16 v[68:71], v[140:143], v[172:175], v[68:71]
	v_mfma_f32_16x16x32_bf16 v[96:99], v[136:139], v[152:155], v[96:99]
	v_mfma_f32_16x16x32_bf16 v[92:95], v[144:147], v[152:155], v[92:95]
	v_mfma_f32_16x16x32_bf16 v[88:91], v[136:139], v[160:163], v[88:91]
	v_mfma_f32_16x16x32_bf16 v[84:87], v[144:147], v[160:163], v[84:87]
	v_mfma_f32_16x16x32_bf16 v[80:83], v[136:139], v[168:171], v[80:83]
	v_mfma_f32_16x16x32_bf16 v[76:79], v[144:147], v[168:171], v[76:79]
	v_mfma_f32_16x16x32_bf16 v[72:75], v[136:139], v[204:207], v[72:75]
	v_mfma_f32_16x16x32_bf16 v[68:71], v[144:147], v[204:207], v[68:71]
	s_barrier
	s_add_i32 s23, s26, s67
	s_mov_b32 m0, s23
	s_add_u32 s24, s44, 0x40080
	s_addc_u32 s25, s45, 0
	global_load_lds_dwordx4 v176, s[24:25]
	s_add_i32 m0, s23, 0x2000
	s_waitcnt vmcnt(5)
	global_load_lds_dwordx4 v180, s[24:25]
	s_barrier
	v_mfma_f32_16x16x32_bf16 v[32:35], v[208:211], v[148:151], v[32:35]
	v_mfma_f32_16x16x32_bf16 v[28:31], v[242:245], v[148:151], v[28:31]
	v_mfma_f32_16x16x32_bf16 v[24:27], v[208:211], v[156:159], v[24:27]
	v_mfma_f32_16x16x32_bf16 v[20:23], v[242:245], v[156:159], v[20:23]
	v_mfma_f32_16x16x32_bf16 v[16:19], v[208:211], v[164:167], v[16:19]
	v_mfma_f32_16x16x32_bf16 v[12:15], v[242:245], v[164:167], v[12:15]
	v_mfma_f32_16x16x32_bf16 v[8:11], v[208:211], v[172:175], v[8:11]
	v_mfma_f32_16x16x32_bf16 v[4:7], v[242:245], v[172:175], v[4:7]
	v_mfma_f32_16x16x32_bf16 v[32:35], v[212:215], v[152:155], v[32:35]
	v_mfma_f32_16x16x32_bf16 v[28:31], v[246:249], v[152:155], v[28:31]
	v_mfma_f32_16x16x32_bf16 v[24:27], v[212:215], v[160:163], v[24:27]
	v_mfma_f32_16x16x32_bf16 v[20:23], v[246:249], v[160:163], v[20:23]
	v_mfma_f32_16x16x32_bf16 v[16:19], v[212:215], v[168:171], v[16:19]
	v_mfma_f32_16x16x32_bf16 v[12:15], v[246:249], v[168:171], v[12:15]
	v_mfma_f32_16x16x32_bf16 v[8:11], v[212:215], v[204:207], v[8:11]
	v_mfma_f32_16x16x32_bf16 v[4:7], v[246:249], v[204:207], v[4:7]
	s_add_i32 s22, s22, 2
	s_add_u32 s0, s0, 0x100
	s_addc_u32 s1, s1, 0
	s_add_u32 s20, s20, 0x100
	s_addc_u32 s21, s21, 0
	s_cmp_gt_u32 s22, 13
	s_barrier
	s_cbranch_scc1 .Lpeel_out_427

.LBB0_499:
	v_readlane_b32 s0, v255, 3
	s_waitcnt vmcnt(0)
	v_readlane_b32 s1, v255, 4
	v_readlane_b32 s56, v254, 63
	s_andn2_b64 vcc, exec, s[0:1]
	v_readlane_b32 s57, v255, 0
	s_mov_b64 s[54:55], 0x3000
	s_mov_b64 s[58:59], 0x6000
	v_xor_b32_e32 v224, 1, v218
	v_xor_b32_e32 v219, 2, v218
	v_xor_b32_e32 v235, 4, v218
	s_cbranch_vccnz .LBB0_501
.LBB0_501:
	v_readlane_b32 s82, v254, 61
	v_readlane_b32 s74, v255, 1
	v_readlane_b32 s83, v254, 62
	v_readlane_b32 s75, v255, 2
	s_mov_b32 s67, 0x8000
	v_mov_b32_e32 v221, v199
	s_barrier
